# v9: strength-reduced tile scheduler at GEMM tile boundary; 4-piece deferred epilogue; FoX unit prologue issues K0/V0/K1/K2 LDS-DMA before the forget-gate image build
# baseline (speedup 1.0000x reference)
.LBB0_276:
	v_mov_b32_e32 v0, s0
	s_waitcnt lgkmcnt(0)
	s_barrier
	ds_read_b32 v0, v0
	s_add_i32 s52, s10, 0x100
	s_ashr_i32 s47, s52, 6
	v_add_u32_e32 v19, 0x200, v181
	v_add_u32_e32 v18, 0x400, v181
	s_waitcnt lgkmcnt(0)
	v_readfirstlane_b32 s1, v0
	s_lshl_b32 s84, s1, 7
	s_lshl_b32 s50, s1, 1
	v_writelane_b32 v241, s16, 30
	v_writelane_b32 v241, s17, 31
	v_writelane_b32 v241, s18, 32
	v_writelane_b32 v241, s19, 33
	v_writelane_b32 v241, s20, 34
	v_writelane_b32 v241, s21, 35
	s_lshl_b64 s[16:17], s[30:31], 24
	s_add_u32 s18, s14, s16
	s_addc_u32 s19, s15, s17
	s_add_u32 s18, s18, s92
	s_addc_u32 s19, s19, s93
	s_add_u32 s20, s71, s16
	s_addc_u32 s21, s72, s17
	s_add_u32 s20, s20, s92
	s_addc_u32 s21, s21, s93
	s_mov_b32 s100, s50
	s_ashr_i32 s101, s50, 31
	s_lshl_b64 s[16:17], s[100:101], 17
	s_add_u32 s18, s18, s16
	s_addc_u32 s19, s19, s17
	s_add_u32 s20, s20, s16
	s_addc_u32 s21, s21, s17
	s_lshl_b32 s100, s69, 4
	v_lshl_add_u32 v198, v178, 11, s100
	v_lshrrev_b32_e32 v199, 2, v178
	v_and_or_b32 v199, s100, 48, v199
	s_ashr_i32 s101, s34, 8
	s_lshl_b32 s101, s101, 5
	v_lshl_add_u32 v199, v199, 10, s101
	v_lshlrev_b32_e32 v200, 3, v32
	v_and_b32_e32 v200, 24, v200
	v_or_b32_e32 v199, v199, v200
	v_lshlrev_b32_e32 v199, 1, v199
	s_lshl_b32 s100, s69, 10
	s_mov_b32 s101, m0
	s_mov_b32 m0, s100
	s_nop 0
	global_load_lds_dwordx4 v198, s[18:19]
	s_add_i32 m0, s100, 0x6000
	s_nop 0
	global_load_lds_dwordx4 v199, s[20:21]
	s_add_u32 s16, s18, 0x20000
	s_addc_u32 s17, s19, 0
	s_add_i32 m0, s100, 0x2000
	s_nop 0
	global_load_lds_dwordx4 v198, s[16:17]
	s_add_u32 s16, s18, 0x40000
	s_addc_u32 s17, s19, 0
	s_add_i32 m0, s100, 0x4000
	s_nop 0
	global_load_lds_dwordx4 v198, s[16:17]
	s_mov_b32 m0, s101
	v_readlane_b32 s16, v241, 30
	v_readlane_b32 s17, v241, 31
	v_readlane_b32 s18, v241, 32
	v_readlane_b32 s19, v241, 33
	v_readlane_b32 s20, v241, 34
	v_readlane_b32 s21, v241, 35
	s_ashr_i32 s85, s84, 31
	s_sub_i32 s78, s47, s50
	s_lshl_b64 s[6:7], s[84:85], 2
	s_add_u32 s10, s39, s6
	s_addc_u32 s11, s54, s7
	s_lshl_b32 s33, s78, 4
	v_cmp_gt_i32_e64 s[8:9], s33, v19
	v_cmp_gt_i32_e64 s[6:7], s33, v18
	v_add_u32_e32 v17, 0x600, v181
	v_cndmask_b32_e64 v2, v181, v19, s[8:9]
	v_lshlrev_b32_e32 v2, 2, v2
	v_ashrrev_i32_e32 v3, 31, v2
	v_lshl_add_u64 v[8:9], v[2:3], 2, s[10:11]
	v_cndmask_b32_e64 v2, v181, v18, s[6:7]
	v_lshlrev_b32_e32 v2, 2, v2
	v_ashrrev_i32_e32 v3, 31, v2
	v_cmp_gt_i32_e32 vcc, s33, v17
	v_lshl_add_u64 v[4:5], v[2:3], 2, s[10:11]
	v_lshlrev_b32_e32 v0, 2, v181
	v_cndmask_b32_e32 v2, v181, v17, vcc
	v_lshlrev_b32_e32 v2, 2, v2
	v_ashrrev_i32_e32 v1, 31, v0
	v_ashrrev_i32_e32 v3, 31, v2
	v_lshl_add_u64 v[0:1], v[0:1], 2, s[10:11]
	v_lshl_add_u64 v[2:3], v[2:3], 2, s[10:11]
	global_load_dwordx4 v[12:15], v[0:1], off
	s_nop 0
	global_load_dwordx4 v[0:3], v[2:3], off
	s_nop 0
	global_load_dwordx4 v[4:7], v[4:5], off
	s_nop 0
	global_load_dwordx4 v[8:11], v[8:9], off
	s_lshl_b32 s1, s1, 2
	s_add_i32 s29, s1, 0
	v_lshlrev_b32_e32 v33, 4, v181
	s_add_i32 s29, s29, 0x1c800
	v_cmp_gt_i32_e64 s[10:11], s33, v181
	s_waitcnt vmcnt(0)
	s_and_saveexec_b64 s[60:61], s[10:11]
	s_cbranch_execz .LBB0_280
	v_ashrrev_i32_e32 v20, 5, v181
	v_lshl_add_u32 v20, v20, 2, s29
	ds_read_b32 v20, v20
	s_waitcnt lgkmcnt(0)
	v_add_f32_e32 v12, v12, v20
	v_mul_f32_e32 v12, 0xbfb8aa3b, v12
	v_cvt_pk_bf16_f32 v21, v12, 0
	v_lshlrev_b32_e32 v21, 16, v21
	v_add_f32_e32 v13, v13, v20
	v_sub_f32_e32 v21, v12, v21
	v_mul_f32_e32 v13, 0xbfb8aa3b, v13
	v_add_f32_e32 v15, v15, v20
	v_cvt_pk_bf16_f32 v12, v12, v21
	v_cvt_pk_bf16_f32 v21, v13, 0
	v_mul_f32_e32 v15, 0xbfb8aa3b, v15
	v_lshlrev_b32_e32 v21, 16, v21
	v_add_f32_e32 v14, v14, v20
	v_cvt_pk_bf16_f32 v20, v15, 0
	v_sub_f32_e32 v21, v13, v21
	v_mul_f32_e32 v14, 0xbfb8aa3b, v14
	v_lshlrev_b32_e32 v20, 16, v20
	v_cvt_pk_bf16_f32 v13, v13, v21
	v_cvt_pk_bf16_f32 v21, v14, 0
	v_sub_f32_e32 v20, v15, v20
	v_lshlrev_b32_e32 v21, 16, v21
	v_cvt_pk_bf16_f32 v15, v15, v20
	v_add_u32_e32 v20, 0, v33
	v_sub_f32_e32 v21, v14, v21
	v_add_u32_e32 v20, 0x14800, v20
	v_cvt_pk_bf16_f32 v14, v14, v21
	ds_write_b128 v20, v[12:15]
	s_or_b64 exec, exec, s[60:61]
	s_and_saveexec_b64 s[10:11], s[8:9]
	s_cbranch_execnz .LBB0_281

.LBB0_284:
	s_or_b64 exec, exec, s[6:7]
	s_lshl_b64 s[6:7], s[30:31], 24
	s_add_u32 s1, s14, s6
	s_addc_u32 s8, s15, s7
	s_add_u32 s6, s71, s6
	s_addc_u32 s7, s72, s7
	s_ashr_i32 s10, s34, 8
	s_lshl_b32 s9, s69, 4
	v_lshrrev_b32_e32 v0, 2, v178
	s_lshl_b32 s11, s10, 5
	s_lshl_b32 s31, s69, 10
	v_and_or_b32 v0, s9, 48, v0
	s_cmp_lg_u32 0, -1
	v_lshl_add_u32 v0, v0, 10, s11
	s_cselect_b32 s11, 0, 0
	s_add_i32 s89, s31, s11
	s_add_u32 s1, s1, s92
	s_addc_u32 s11, s8, s93
	s_add_u32 s29, s6, s92
	s_addc_u32 s30, s7, s93
	s_lshl_b32 s6, s99, 3
	s_add_i32 s6, s6, 0
	s_lshl_b32 s7, s10, 2
	s_add_i32 s6, s6, s7
	v_lshlrev_b32_e32 v1, 3, v32
	s_add_i32 s6, s6, 0x1c800
	s_ashr_i32 s51, s50, 31
	v_and_b32_e32 v183, 24, v1
	v_mov_b32_e32 v1, s6
	s_add_i32 s79, s89, 0x6000
	s_lshl_b64 s[6:7], s[50:51], 17
	s_add_u32 s8, s1, s6
	v_lshl_add_u32 v190, v178, 11, s9
	s_addc_u32 s9, s11, s7
	ds_read_b32 v1, v1
	s_add_u32 s10, s29, s6
	v_or_b32_e32 v0, v0, v183
	s_waitcnt lgkmcnt(0)
	s_barrier
	s_addc_u32 s11, s30, s7
	s_mov_b32 s1, m0
	s_mov_b32 m0, s89
	s_nop 0
	s_nop 0
	s_mov_b32 m0, s1
	v_lshlrev_b32_e32 v191, 1, v0
	s_mov_b32 s1, m0
	s_mov_b32 m0, s79
	s_nop 0
	s_nop 0
	s_mov_b32 m0, s1
	s_add_u32 s6, s8, 0x20000
	s_addc_u32 s7, s9, 0
	s_add_i32 s1, s89, 0x2000
	s_mov_b32 s29, m0
	s_mov_b32 m0, s1
	s_nop 0
	s_nop 0
	s_mov_b32 m0, s29
	s_add_u32 s6, s8, 0x40000
	v_add_f32_e32 v0, v16, v1
	v_lshl_add_u32 v1, v179, 2, 0
	s_addc_u32 s7, s9, 0
	s_add_i32 s1, s89, 0x4000
	s_mov_b32 s29, m0
	s_mov_b32 m0, s1
	s_nop 0
	s_nop 0
	s_mov_b32 m0, s29
	v_add_u32_e32 v189, 0x14800, v1
	s_waitcnt vmcnt(3) lgkmcnt(0)
	s_barrier
	ds_read2_b32 v[20:21], v189 offset1:32
	v_mul_f32_e32 v0, 0x3fb8aa3b, v0
	v_cvt_pk_bf16_f32 v1, v0, 0
	v_lshlrev_b32_e32 v40, 16, v1
	v_sub_f32_e32 v1, v0, v40
	s_mov_b32 s39, s38
	v_cvt_pk_bf16_f32 v41, v0, v1
	v_mov_b64_e32 v[0:1], s[36:37]
	v_mov_b64_e32 v[2:3], s[38:39]
	s_waitcnt lgkmcnt(0)
	v_mov_b32_e32 v0, v20
	v_mov_b64_e32 v[16:17], s[36:37]
	v_mov_b32_e32 v16, v21
	v_lshlrev_b32_e32 v20, 10, v180
	v_lshlrev_b32_e32 v21, 4, v179
	v_cmp_gt_u32_e64 s[6:7], 32, v178
	v_add3_u32 v192, 0, v20, v21
	v_mov_b32_e32 v100, v101
	v_cndmask_b32_e64 v98, 0, v221, s[6:7]
	v_cndmask_b32_e64 v99, 0, v41, s[6:7]
	ds_read_b128 v[34:37], v192
	v_mov_b64_e32 v[18:19], s[38:39]
	v_mfma_f32_32x32x16_bf16 v[0:15], v[0:3], v[98:101], 0
	v_or_b32_e32 v187, s28, v179
	s_cmp_gt_i32 s78, 4
	v_lshlrev_b32_e32 v184, 2, v180
	s_waitcnt lgkmcnt(0)
	v_mfma_f32_32x32x16_bf16 v[0:15], v[34:37], v[114:117], v[0:15]
	ds_read_b128 v[34:37], v192 offset:512
	v_mfma_f32_32x32x16_bf16 v[16:31], v[16:19], v[98:101], 0
	s_waitcnt lgkmcnt(0)
	v_mfma_f32_32x32x16_bf16 v[16:31], v[34:37], v[114:117], v[16:31]
	ds_read_b128 v[34:37], v192 offset:2048
	s_waitcnt lgkmcnt(0)
	v_mfma_f32_32x32x16_bf16 v[0:15], v[34:37], v[110:113], v[0:15]
	ds_read_b128 v[34:37], v192 offset:2560
	s_waitcnt lgkmcnt(0)
	v_mfma_f32_32x32x16_bf16 v[16:31], v[34:37], v[110:113], v[16:31]
	ds_read_b128 v[34:37], v192 offset:4096
	s_waitcnt lgkmcnt(0)
	v_mfma_f32_32x32x16_bf16 v[0:15], v[34:37], v[106:109], v[0:15]
	ds_read_b128 v[34:37], v192 offset:4608
	s_waitcnt lgkmcnt(0)
	v_mfma_f32_32x32x16_bf16 v[16:31], v[34:37], v[106:109], v[16:31]
	ds_read_b128 v[34:37], v192 offset:6144
	s_waitcnt lgkmcnt(0)
	v_mfma_f32_32x32x16_bf16 v[0:15], v[34:37], v[102:105], v[0:15]
	ds_read_b128 v[36:39], v192 offset:6656
	v_and_b32_e32 v34, 0xffff0000, v41
	v_add_f32_e32 v34, v40, v34
	s_waitcnt lgkmcnt(0)
	v_mfma_f32_32x32x16_bf16 v[16:31], v[36:39], v[102:105], v[16:31]
	s_nop 15
	s_nop 7
	s_cbranch_scc1 .LBB0_286
	s_lshl_b32 s1, s78, 6
	v_subrev_u32_e32 v35, s1, v184
	v_add_u32_e32 v37, 0x120, v35
	v_add_u32_e32 v36, 0x100, v35
	v_cmp_le_i32_e32 vcc, v37, v187
	s_nop 5
	v_cndmask_b32_e32 v16, v220, v16, vcc
	v_cmp_lt_i32_e32 vcc, v36, v187
	s_nop 1
	v_cndmask_b32_e32 v1, v220, v1, vcc
	v_cmp_le_i32_e32 vcc, v36, v187
	v_add_u32_e32 v36, 0x121, v35
	s_nop 0
	v_cndmask_b32_e32 v0, v220, v0, vcc
	v_cmp_le_i32_e32 vcc, v36, v187
	v_add_u32_e32 v36, 0x102, v35
	s_nop 0
	v_cndmask_b32_e32 v17, v220, v17, vcc
	v_cmp_le_i32_e32 vcc, v36, v187
	v_add_u32_e32 v36, 0x122, v35
	s_nop 0
	v_cndmask_b32_e32 v2, v220, v2, vcc
	v_cmp_le_i32_e32 vcc, v36, v187
	v_add_u32_e32 v36, 0x103, v35
	s_nop 0
	v_cndmask_b32_e32 v18, v220, v18, vcc
	v_cmp_le_i32_e32 vcc, v36, v187
	v_add_u32_e32 v36, 0x123, v35
	s_nop 0
	v_cndmask_b32_e32 v3, v220, v3, vcc
	v_cmp_le_i32_e32 vcc, v36, v187
	v_add_u32_e32 v36, 0x108, v35
	s_nop 0
	v_cndmask_b32_e32 v19, v220, v19, vcc
	v_cmp_le_i32_e32 vcc, v36, v187
	v_add_u32_e32 v36, 0x128, v35
	s_nop 0
	v_cndmask_b32_e32 v4, v220, v4, vcc
	v_cmp_le_i32_e32 vcc, v36, v187
	v_add_u32_e32 v36, 0x109, v35
	s_nop 0
	v_cndmask_b32_e32 v20, v220, v20, vcc
	v_cmp_le_i32_e32 vcc, v36, v187
	v_add_u32_e32 v36, 0x129, v35
	s_nop 0
	v_cndmask_b32_e32 v5, v220, v5, vcc
	v_cmp_le_i32_e32 vcc, v36, v187
	v_add_u32_e32 v36, 0x10a, v35
	s_nop 0
	v_cndmask_b32_e32 v21, v220, v21, vcc
	v_cmp_le_i32_e32 vcc, v36, v187
	v_add_u32_e32 v36, 0x12a, v35
	s_nop 0
	v_cndmask_b32_e32 v6, v220, v6, vcc
	v_cmp_le_i32_e32 vcc, v36, v187
	v_add_u32_e32 v36, 0x10b, v35
	s_nop 0
	v_cndmask_b32_e32 v22, v220, v22, vcc
	v_cmp_le_i32_e32 vcc, v36, v187
	v_add_u32_e32 v36, 0x12b, v35
	s_nop 0
	v_cndmask_b32_e32 v7, v220, v7, vcc
	v_cmp_le_i32_e32 vcc, v36, v187
	v_add_u32_e32 v36, 0x110, v35
	s_nop 0
	v_cndmask_b32_e32 v23, v220, v23, vcc
	v_cmp_le_i32_e32 vcc, v36, v187
	v_add_u32_e32 v36, 0x130, v35
	s_nop 0
	v_cndmask_b32_e32 v8, v220, v8, vcc
	v_cmp_le_i32_e32 vcc, v36, v187
	v_add_u32_e32 v36, 0x111, v35
	s_nop 0
	v_cndmask_b32_e32 v24, v220, v24, vcc
	v_cmp_le_i32_e32 vcc, v36, v187
	v_add_u32_e32 v36, 0x131, v35
	s_nop 0
	v_cndmask_b32_e32 v9, v220, v9, vcc
	v_cmp_le_i32_e32 vcc, v36, v187
	v_add_u32_e32 v36, 0x112, v35
	s_nop 0
	v_cndmask_b32_e32 v25, v220, v25, vcc
	v_cmp_le_i32_e32 vcc, v36, v187
	v_add_u32_e32 v36, 0x132, v35
	s_nop 0
	v_cndmask_b32_e32 v10, v220, v10, vcc
	v_cmp_le_i32_e32 vcc, v36, v187
	v_add_u32_e32 v36, 0x113, v35
	s_nop 0
	v_cndmask_b32_e32 v26, v220, v26, vcc
	v_cmp_le_i32_e32 vcc, v36, v187
	v_add_u32_e32 v36, 0x133, v35
	s_nop 0
	v_cndmask_b32_e32 v11, v220, v11, vcc
	v_cmp_le_i32_e32 vcc, v36, v187
	v_add_u32_e32 v36, 0x118, v35
	s_nop 0
	v_cndmask_b32_e32 v27, v220, v27, vcc
	v_cmp_le_i32_e32 vcc, v36, v187
	v_add_u32_e32 v36, 0x138, v35
	s_nop 0
	v_cndmask_b32_e32 v12, v220, v12, vcc
	v_cmp_le_i32_e32 vcc, v36, v187
	v_add_u32_e32 v36, 0x119, v35
	s_nop 0
	v_cndmask_b32_e32 v28, v220, v28, vcc
	v_cmp_le_i32_e32 vcc, v36, v187
	v_add_u32_e32 v36, 0x139, v35
	s_nop 0
	v_cndmask_b32_e32 v13, v220, v13, vcc
	v_cmp_le_i32_e32 vcc, v36, v187
	v_add_u32_e32 v36, 0x11a, v35
	s_nop 0
	v_cndmask_b32_e32 v29, v220, v29, vcc
	v_cmp_le_i32_e32 vcc, v36, v187
	v_add_u32_e32 v36, 0x13a, v35
	s_nop 0
	v_cndmask_b32_e32 v14, v220, v14, vcc
	v_cmp_le_i32_e32 vcc, v36, v187
	v_add_u32_e32 v36, 0x11b, v35
	v_add_u32_e32 v35, 0x13b, v35
	v_cndmask_b32_e32 v30, v220, v30, vcc
	v_cmp_le_i32_e32 vcc, v36, v187
	s_nop 1
	v_cndmask_b32_e32 v15, v220, v15, vcc
	v_cmp_le_i32_e32 vcc, v35, v187
	s_nop 1
	v_cndmask_b32_e32 v31, v220, v31, vcc

.LBB0_387:
	s_andn2_b64 vcc, exec, s[12:13]
	s_cbranch_vccnz .LBB0_481
	v_writelane_b32 v157, s0, 0
	v_writelane_b32 v157, s2, 1
	v_writelane_b32 v157, s3, 2
	v_writelane_b32 v157, s32, 3
	v_writelane_b32 v157, s36, 4
	v_writelane_b32 v157, s37, 5
	v_writelane_b32 v157, s46, 6
	v_writelane_b32 v157, s53, 7
	v_writelane_b32 v157, s56, 8
	v_writelane_b32 v157, s82, 9
	v_writelane_b32 v157, s90, 10
	v_writelane_b32 v157, s91, 11
	v_writelane_b32 v157, s97, 12
	s_mov_b32 s37, 0
	v_readlane_b32 s53, v241, 5
	s_and_b32 s100, s26, 0xff
	s_and_b32 s101, s48, 7
	s_or_b32 s100, s100, s101
	s_xor_b32 s101, s83, 0x100
	s_or_b32 s100, s100, s101
	s_cmp_eq_u32 s100, 0
	s_cselect_b32 s56, 1, 0
	s_cmp_lt_u32 s53, 4
	s_cselect_b32 s56, 0, s56
	v_ashrrev_i32_e32 v1, 31, v225
	v_lshrrev_b32_e32 v1, 26, v1
	v_add_u32_e32 v1, v225, v1
	v_ashrrev_i32_e32 v9, 6, v1
	v_bfe_i32 v1, v225, 27, 1
	v_lshlrev_b32_e32 v0, 4, v225
	v_lshrrev_b32_e32 v1, 22, v1
	v_add_u32_e32 v1, v0, v1
	v_and_b32_e32 v1, 0xfffffc00, v1
	v_sub_u32_e32 v1, v0, v1
	v_lshrrev_b32_e32 v2, 4, v1
	v_bitop3_b32 v1, v2, v1, 32 bitop3:0x6c
	v_ashrrev_i32_e32 v3, 31, v1
	v_lshrrev_b32_e32 v3, 26, v3
	v_add_u32_e32 v3, v1, v3
	v_lshlrev_b32_e32 v2, 3, v9
	v_ashrrev_i32_e32 v10, 6, v3
	v_and_b32_e32 v3, 0xc0, v3
	v_and_b32_e32 v2, -16, v2
	v_sub_u32_e32 v1, v1, v3
	v_add_u32_e32 v2, v10, v2
	v_ashrrev_i16_sdwa v1, v219, sext(v1) dst_sel:DWORD dst_unused:UNUSED_PAD src0_sel:DWORD src1_sel:BYTE_0
	v_lshlrev_b32_e32 v4, 5, v9
	v_bfe_i32 v11, v1, 0, 16
	v_lshlrev_b32_e32 v1, 1, v2
	v_lshrrev_b32_e32 v3, 2, v2
	v_and_b32_e32 v5, 3, v10
	s_mov_b32 s1, 0x1fffe0
	v_and_b32_e32 v4, 32, v4
	v_and_b32_e32 v1, 24, v1
	v_and_b32_e32 v3, 4, v3
	v_and_or_b32 v5, v2, s1, v5
	v_or3_b32 v1, v5, v3, v1
	v_add_lshl_u32 v3, v4, v11, 1
	v_add_u32_e32 v0, 0x2000, v0
	v_lshl_add_u32 v132, v1, 11, v3
	v_ashrrev_i32_e32 v1, 31, v0
	v_lshrrev_b32_e32 v1, 22, v1
	v_add_u32_e32 v1, v0, v1
	v_ashrrev_i32_e32 v12, 10, v1
	v_mul_i32_i24_e32 v1, 0x400, v12
	v_sub_u32_e32 v0, v0, v1
	v_lshrrev_b32_e32 v1, 4, v0
	v_bitop3_b32 v0, v1, v0, 32 bitop3:0x6c
	v_lshl_add_u32 v130, v2, 11, v3
	v_ashrrev_i32_e32 v2, 31, v0
	v_lshrrev_b32_e32 v2, 26, v2
	v_lshlrev_b32_e32 v1, 3, v12
	v_add_u32_e32 v2, v0, v2
	v_and_b32_e32 v1, -16, v1
	v_ashrrev_i32_e32 v13, 6, v2
	v_add_u32_e32 v1, v13, v1
	v_and_b32_e32 v2, 0xc0, v2
	v_and_b32_e32 v4, 3, v13
	s_ashr_i32 s29, s28, 6
	s_ashr_i32 s41, s40, 31
	s_ashr_i32 s11, s10, 31
	v_sub_u32_e32 v0, v0, v2
	v_and_or_b32 v4, v1, s1, v4
	s_ashr_i32 s1, s28, 8
	s_lshl_b32 s34, s29, 10
	s_lshl_b64 s[12:13], s[40:41], 19
	s_lshl_b64 s[14:15], s[10:11], 19
	v_ashrrev_i16_sdwa v0, v219, sext(v0) dst_sel:DWORD dst_unused:UNUSED_PAD src0_sel:DWORD src1_sel:BYTE_0
	s_add_u32 s14, s20, s14
	v_lshlrev_b32_e32 v3, 5, v12
	v_bfe_i32 v14, v0, 0, 16
	v_lshlrev_b32_e32 v0, 1, v1
	v_lshrrev_b32_e32 v2, 2, v1
	s_addc_u32 s15, s21, s15
	s_add_i32 s41, s34, 0
	v_and_b32_e32 v3, 32, v3
	v_and_b32_e32 v0, 24, v0
	v_and_b32_e32 v2, 4, v2
	s_add_i32 m0, s41, 0x10000
	v_or3_b32 v0, v4, v2, v0
	v_add_lshl_u32 v2, v3, v14, 1
	global_load_lds_dwordx4 v132, s[14:15]
	s_add_i32 m0, s41, 0x12000
	v_lshl_add_u32 v136, v0, 11, v2
	s_add_u32 s30, s14, 0x40000
	global_load_lds_dwordx4 v136, s[14:15]
	s_addc_u32 s31, s15, 0
	s_add_i32 m0, s41, 0x14000
	v_lshl_add_u32 v134, v1, 11, v2
	global_load_lds_dwordx4 v132, s[30:31]
	s_add_i32 m0, s41, 0x16000
	s_add_u32 s12, s62, s12
	s_addc_u32 s13, s63, s13
	s_add_i32 s60, s41, 0x2000
	global_load_lds_dwordx4 v136, s[30:31]
	s_mov_b32 m0, s41
	s_add_u32 s30, s12, 0x40000
	global_load_lds_dwordx4 v130, s[12:13]
	s_mov_b32 m0, s60
	s_addc_u32 s31, s13, 0
	s_add_i32 s61, s41, 0x4000
	global_load_lds_dwordx4 v134, s[12:13]
	s_mov_b32 m0, s61
	s_add_i32 s69, s41, 0x6000
	global_load_lds_dwordx4 v130, s[30:31]
	s_mov_b32 m0, s69
	v_mov_b32_e32 v133, v101
	global_load_lds_dwordx4 v134, s[30:31]
	v_mov_b32_e32 v137, v101
	v_mov_b32_e32 v131, v101
	v_mov_b32_e32 v135, v101
	s_cmp_eq_u32 s1, 1
	v_lshl_add_u64 v[6:7], s[14:15], 0, v[132:133]
	v_lshl_add_u64 v[4:5], s[14:15], 0, v[136:137]
	v_lshl_add_u64 v[0:1], s[12:13], 0, v[130:131]
	s_cselect_b64 s[42:43], -1, 0
	s_cmp_lg_u32 s1, 1
	v_lshl_add_u64 v[2:3], s[12:13], 0, v[134:135]
	s_cbranch_scc1 .LBB0_390
	s_barrier

.LBB0_393:
	s_cmp_lg_u32 s56, 0
	s_cbranch_scc0 .Lmy_b16_gen393
	s_add_i32 s93, s93, 1
	s_lshr_b32 s1, s26, 8
	s_cmp_lt_u32 s93, s1
	s_cselect_b64 s[8:9], -1, 0
	s_cbranch_scc0 .LBB0_395
	s_add_i32 s72, s10, 4
	s_sub_i32 s1, s72, s53
	s_add_i32 s28, s40, 8
	s_cmp_ge_i32 s1, 0
	s_cselect_b32 s72, s1, s72
	s_cselect_b32 s74, s28, s40
	s_branch .LBB0_395

.Lmy_b16_pdefer:
	s_add_u32 s1, s12, 0xfffc0080
	s_addc_u32 s14, s13, -1
	s_add_i32 s33, 0, 0x10000
	s_cmp_eq_u32 s73, 12
	s_cselect_b32 s29, s11, s14
	s_cselect_b32 s28, s30, s1
	v_add_u32_e32 v100, s33, v154
	s_cselect_b32 s15, s31, s55
	s_cselect_b32 s14, s47, s54
	s_add_i32 s1, 0, 0x14000
	ds_read_b128 v[144:147], v100
	ds_read_b128 v[148:151], v100 offset:1024
	ds_read_b128 v[158:161], v100 offset:2048
	ds_read_b128 v[162:165], v100 offset:3072
	v_add_u32_e32 v100, s1, v154
	ds_read_b128 v[166:169], v100
	ds_read_b128 v[170:173], v100 offset:1024
	ds_read_b128 v[174:177], v100 offset:2048
	ds_read_b128 v[178:181], v100 offset:3072
	v_lshl_add_u64 v[152:153], s[12:13], 0, v[140:141]
	s_add_i32 m0, s41, 0xc000
	ds_read_b128 v[182:185], v156
	ds_read_b128 v[186:189], v156 offset:1024
	ds_read_b128 v[190:193], v156 offset:2048
	ds_read_b128 v[194:197], v156 offset:3072
	ds_read_b128 v[198:201], v156 offset:4096
	ds_read_b128 v[202:205], v156 offset:5120
	ds_read_b128 v[208:211], v156 offset:6144
	ds_read_b128 v[226:229], v156 offset:7168
	global_load_lds_dwordx4 v[152:153], off
	v_lshl_add_u64 v[152:153], s[12:13], 0, v[142:143]
	s_add_i32 m0, s41, 0xe000
	s_nop 0
	global_load_lds_dwordx4 v[152:153], off
	v_and_b32_e32 v100, 3, v224
	v_lshlrev_b32_e32 v100, 6, v100
	v_and_or_b32 v100, v224, 60, v100
	v_mov_b32_e32 v152, v247
	v_fmamk_f32 v234, v236, 0x3a800000, v207
	v_rsq_f32_e32 v234, v234
	s_nop 0
	v_mul_f32_e32 v234, s36, v234
	v_pk_mul_f32 v[126:127], v[126:127], v[234:235] op_sel_hi:[1,0]
	v_pk_mul_f32 v[128:129], v[128:129], v[234:235] op_sel_hi:[1,0]
	v_pk_mul_f32 v[122:123], v[122:123], v[234:235] op_sel_hi:[1,0]
	v_pk_mul_f32 v[124:125], v[124:125], v[234:235] op_sel_hi:[1,0]
	v_cvt_pk_bf16_f32 v126, v126, v127
	v_cvt_pk_bf16_f32 v127, v128, v129
	v_cvt_pk_bf16_f32 v128, v122, v123
	v_cvt_pk_bf16_f32 v129, v124, v125
	ds_bpermute_b32 v122, v100, v126
	ds_bpermute_b32 v123, v100, v127
	ds_bpermute_b32 v124, v100, v128
	ds_bpermute_b32 v125, v100, v129
	v_fmamk_f32 v234, v237, 0x3a800000, v207
	v_rsq_f32_e32 v234, v234
	s_nop 0
	v_mul_f32_e32 v234, s36, v234
	v_pk_mul_f32 v[110:111], v[110:111], v[234:235] op_sel_hi:[1,0]
	v_pk_mul_f32 v[112:113], v[112:113], v[234:235] op_sel_hi:[1,0]
	v_pk_mul_f32 v[106:107], v[106:107], v[234:235] op_sel_hi:[1,0]
	v_pk_mul_f32 v[108:109], v[108:109], v[234:235] op_sel_hi:[1,0]
	v_cvt_pk_bf16_f32 v110, v110, v111
	v_cvt_pk_bf16_f32 v111, v112, v113
	v_cvt_pk_bf16_f32 v112, v106, v107
	v_cvt_pk_bf16_f32 v113, v108, v109
	ds_bpermute_b32 v106, v100, v110
	ds_bpermute_b32 v107, v100, v111
	ds_bpermute_b32 v108, v100, v112
	ds_bpermute_b32 v109, v100, v113
	s_waitcnt lgkmcnt(4)
	global_store_dwordx4 v152, v[122:125], s[2:3] nt
	v_add_u32_e32 v152, s0, v152
	v_fmamk_f32 v234, v238, 0x3a800000, v207
	v_rsq_f32_e32 v234, v234
	s_nop 0
	v_mul_f32_e32 v234, s36, v234
	v_pk_mul_f32 v[92:93], v[92:93], v[234:235] op_sel_hi:[1,0]
	v_pk_mul_f32 v[94:95], v[94:95], v[234:235] op_sel_hi:[1,0]
	v_pk_mul_f32 v[88:89], v[88:89], v[234:235] op_sel_hi:[1,0]
	v_pk_mul_f32 v[90:91], v[90:91], v[234:235] op_sel_hi:[1,0]
	v_cvt_pk_bf16_f32 v92, v92, v93
	v_cvt_pk_bf16_f32 v93, v94, v95
	v_cvt_pk_bf16_f32 v94, v88, v89
	v_cvt_pk_bf16_f32 v95, v90, v91
	ds_bpermute_b32 v88, v100, v92
	ds_bpermute_b32 v89, v100, v93
	ds_bpermute_b32 v90, v100, v94
	ds_bpermute_b32 v91, v100, v95
	s_waitcnt lgkmcnt(4)
	global_store_dwordx4 v152, v[106:109], s[2:3] nt
	v_add_u32_e32 v152, s0, v152
	v_fmamk_f32 v234, v239, 0x3a800000, v207
	v_rsq_f32_e32 v234, v234
	s_nop 0
	v_mul_f32_e32 v234, s36, v234
	v_pk_mul_f32 v[76:77], v[76:77], v[234:235] op_sel_hi:[1,0]
	v_pk_mul_f32 v[78:79], v[78:79], v[234:235] op_sel_hi:[1,0]
	v_pk_mul_f32 v[72:73], v[72:73], v[234:235] op_sel_hi:[1,0]
	v_pk_mul_f32 v[74:75], v[74:75], v[234:235] op_sel_hi:[1,0]
	v_cvt_pk_bf16_f32 v76, v76, v77
	v_cvt_pk_bf16_f32 v77, v78, v79
	v_cvt_pk_bf16_f32 v78, v72, v73
	v_cvt_pk_bf16_f32 v79, v74, v75
	ds_bpermute_b32 v72, v100, v76
	ds_bpermute_b32 v73, v100, v77
	ds_bpermute_b32 v74, v100, v78
	ds_bpermute_b32 v75, v100, v79
	s_waitcnt lgkmcnt(4)
	global_store_dwordx4 v152, v[88:91], s[2:3] nt
	v_add_u32_e32 v152, s0, v152
	s_waitcnt lgkmcnt(0)
	global_store_dwordx4 v152, v[72:75], s[2:3] nt
	s_waitcnt vmcnt(12)
	s_waitcnt lgkmcnt(0)
	s_barrier
	s_setprio 1
	s_waitcnt lgkmcnt(0)
	v_mfma_f32_16x16x32_bf16 v[126:129], v[144:147], v[182:185], 0
	v_add_u32_e32 v153, s32, v247
	v_fmamk_f32 v230, v236, 0x3a800000, v207
	v_rsq_f32_e32 v230, v230
	s_nop 0
	v_mfma_f32_16x16x32_bf16 v[122:125], v[158:161], v[182:185], 0
	v_mul_f32_e32 v230, s36, v230
	v_pk_mul_f32 v[118:119], v[118:119], v[230:231] op_sel_hi:[1,0]
	v_pk_mul_f32 v[120:121], v[120:121], v[230:231] op_sel_hi:[1,0]
	v_pk_mul_f32 v[114:115], v[114:115], v[230:231] op_sel_hi:[1,0]
	v_pk_mul_f32 v[116:117], v[116:117], v[230:231] op_sel_hi:[1,0]
	v_mfma_f32_16x16x32_bf16 v[110:113], v[144:147], v[190:193], 0
	v_cvt_pk_bf16_f32 v118, v118, v119
	v_cvt_pk_bf16_f32 v119, v120, v121
	v_cvt_pk_bf16_f32 v120, v114, v115
	v_cvt_pk_bf16_f32 v121, v116, v117
	ds_bpermute_b32 v114, v100, v118
	v_mfma_f32_16x16x32_bf16 v[106:109], v[158:161], v[190:193], 0
	ds_bpermute_b32 v115, v100, v119
	ds_bpermute_b32 v116, v100, v120
	ds_bpermute_b32 v117, v100, v121
	v_fmamk_f32 v230, v237, 0x3a800000, v207
	v_rsq_f32_e32 v230, v230
	v_mfma_f32_16x16x32_bf16 v[92:95], v[144:147], v[198:201], 0
	s_nop 0
	v_mul_f32_e32 v230, s36, v230
	v_pk_mul_f32 v[102:103], v[102:103], v[230:231] op_sel_hi:[1,0]
	v_pk_mul_f32 v[104:105], v[104:105], v[230:231] op_sel_hi:[1,0]
	v_mfma_f32_16x16x32_bf16 v[88:91], v[158:161], v[198:201], 0
	v_pk_mul_f32 v[96:97], v[96:97], v[230:231] op_sel_hi:[1,0]
	v_pk_mul_f32 v[98:99], v[98:99], v[230:231] op_sel_hi:[1,0]
	v_cvt_pk_bf16_f32 v102, v102, v103
	v_cvt_pk_bf16_f32 v103, v104, v105
	v_cvt_pk_bf16_f32 v104, v96, v97
	v_mfma_f32_16x16x32_bf16 v[76:79], v[144:147], v[208:211], 0
	v_cvt_pk_bf16_f32 v105, v98, v99
	ds_bpermute_b32 v96, v100, v102
	ds_bpermute_b32 v97, v100, v103
	ds_bpermute_b32 v98, v100, v104
	ds_bpermute_b32 v99, v100, v105
	v_mfma_f32_16x16x32_bf16 v[72:75], v[158:161], v[208:211], 0
	s_waitcnt lgkmcnt(4)
	global_store_dwordx4 v153, v[114:117], s[2:3] nt
	v_add_u32_e32 v153, s0, v153
	v_fmamk_f32 v230, v238, 0x3a800000, v207
	v_rsq_f32_e32 v230, v230
	v_mfma_f32_16x16x32_bf16 v[126:129], v[148:151], v[186:189], v[126:129]
	s_nop 0
	v_mul_f32_e32 v230, s36, v230
	v_pk_mul_f32 v[84:85], v[84:85], v[230:231] op_sel_hi:[1,0]
	v_pk_mul_f32 v[86:87], v[86:87], v[230:231] op_sel_hi:[1,0]
	v_mfma_f32_16x16x32_bf16 v[122:125], v[162:165], v[186:189], v[122:125]
	v_pk_mul_f32 v[80:81], v[80:81], v[230:231] op_sel_hi:[1,0]
	v_pk_mul_f32 v[82:83], v[82:83], v[230:231] op_sel_hi:[1,0]
	v_cvt_pk_bf16_f32 v84, v84, v85
	v_cvt_pk_bf16_f32 v85, v86, v87
	v_cvt_pk_bf16_f32 v86, v80, v81
	v_mfma_f32_16x16x32_bf16 v[110:113], v[148:151], v[194:197], v[110:113]
	v_cvt_pk_bf16_f32 v87, v82, v83
	ds_bpermute_b32 v80, v100, v84
	ds_bpermute_b32 v81, v100, v85
	ds_bpermute_b32 v82, v100, v86
	ds_bpermute_b32 v83, v100, v87
	v_mfma_f32_16x16x32_bf16 v[106:109], v[162:165], v[194:197], v[106:109]
	s_waitcnt lgkmcnt(4)
	global_store_dwordx4 v153, v[96:99], s[2:3] nt
	v_add_u32_e32 v153, s0, v153
	v_fmamk_f32 v230, v239, 0x3a800000, v207
	v_rsq_f32_e32 v230, v230
	v_mfma_f32_16x16x32_bf16 v[92:95], v[148:151], v[202:205], v[92:95]
	s_nop 0
	v_mul_f32_e32 v230, s36, v230
	v_pk_mul_f32 v[68:69], v[68:69], v[230:231] op_sel_hi:[1,0]
	v_pk_mul_f32 v[70:71], v[70:71], v[230:231] op_sel_hi:[1,0]
	v_mfma_f32_16x16x32_bf16 v[88:91], v[162:165], v[202:205], v[88:91]
	v_pk_mul_f32 v[64:65], v[64:65], v[230:231] op_sel_hi:[1,0]
	v_pk_mul_f32 v[66:67], v[66:67], v[230:231] op_sel_hi:[1,0]
	v_cvt_pk_bf16_f32 v68, v68, v69
	v_cvt_pk_bf16_f32 v69, v70, v71
	v_cvt_pk_bf16_f32 v70, v64, v65
	v_mfma_f32_16x16x32_bf16 v[76:79], v[148:151], v[226:229], v[76:79]
	v_cvt_pk_bf16_f32 v71, v66, v67
	ds_bpermute_b32 v64, v100, v68
	ds_bpermute_b32 v65, v100, v69
	ds_bpermute_b32 v66, v100, v70
	ds_bpermute_b32 v67, v100, v71
	v_mfma_f32_16x16x32_bf16 v[72:75], v[162:165], v[226:229], v[72:75]
	s_waitcnt lgkmcnt(4)
	global_store_dwordx4 v153, v[80:83], s[2:3] nt
	v_add_u32_e32 v153, s0, v153
	s_waitcnt lgkmcnt(0)
	global_store_dwordx4 v153, v[64:67], s[2:3] nt
	s_setprio 0
	s_setprio 1
	v_mfma_f32_16x16x32_bf16 v[118:121], v[166:169], v[182:185], 0
	v_mov_b32_e32 v152, v247
	v_fmamk_f32 v234, v240, 0x3a800000, v207
	v_rsq_f32_e32 v234, v234
	s_nop 0
	v_mfma_f32_16x16x32_bf16 v[114:117], v[174:177], v[182:185], 0
	v_mul_f32_e32 v234, s36, v234
	v_pk_mul_f32 v[60:61], v[60:61], v[234:235] op_sel_hi:[1,0]
	v_pk_mul_f32 v[62:63], v[62:63], v[234:235] op_sel_hi:[1,0]
	v_pk_mul_f32 v[56:57], v[56:57], v[234:235] op_sel_hi:[1,0]
	v_pk_mul_f32 v[58:59], v[58:59], v[234:235] op_sel_hi:[1,0]
	v_mfma_f32_16x16x32_bf16 v[102:105], v[166:169], v[190:193], 0
	v_cvt_pk_bf16_f32 v60, v60, v61
	v_cvt_pk_bf16_f32 v61, v62, v63
	v_cvt_pk_bf16_f32 v62, v56, v57
	v_cvt_pk_bf16_f32 v63, v58, v59
	ds_bpermute_b32 v56, v100, v60
	v_mfma_f32_16x16x32_bf16 v[96:99], v[174:177], v[190:193], 0
	ds_bpermute_b32 v57, v100, v61
	ds_bpermute_b32 v58, v100, v62
	ds_bpermute_b32 v59, v100, v63
	v_fmamk_f32 v234, v244, 0x3a800000, v207
	v_rsq_f32_e32 v234, v234
	v_mfma_f32_16x16x32_bf16 v[84:87], v[166:169], v[198:201], 0
	s_nop 0
	v_mul_f32_e32 v234, s36, v234
	v_pk_mul_f32 v[44:45], v[44:45], v[234:235] op_sel_hi:[1,0]
	v_pk_mul_f32 v[46:47], v[46:47], v[234:235] op_sel_hi:[1,0]
	v_mfma_f32_16x16x32_bf16 v[80:83], v[174:177], v[198:201], 0
	v_pk_mul_f32 v[40:41], v[40:41], v[234:235] op_sel_hi:[1,0]
	v_pk_mul_f32 v[42:43], v[42:43], v[234:235] op_sel_hi:[1,0]
	v_cvt_pk_bf16_f32 v44, v44, v45
	v_cvt_pk_bf16_f32 v45, v46, v47
	v_cvt_pk_bf16_f32 v46, v40, v41
	v_mfma_f32_16x16x32_bf16 v[68:71], v[166:169], v[208:211], 0
	v_cvt_pk_bf16_f32 v47, v42, v43
	ds_bpermute_b32 v40, v100, v44
	ds_bpermute_b32 v41, v100, v45
	ds_bpermute_b32 v42, v100, v46
	ds_bpermute_b32 v43, v100, v47
	v_mfma_f32_16x16x32_bf16 v[64:67], v[174:177], v[208:211], 0
	s_waitcnt lgkmcnt(4)
	global_store_dwordx4 v152, v[56:59], s[90:91] nt
	v_add_u32_e32 v152, s0, v152
	v_fmamk_f32 v234, v245, 0x3a800000, v207
	v_rsq_f32_e32 v234, v234
	v_mfma_f32_16x16x32_bf16 v[118:121], v[170:173], v[186:189], v[118:121]
	s_nop 0
	v_mul_f32_e32 v234, s36, v234
	v_pk_mul_f32 v[28:29], v[28:29], v[234:235] op_sel_hi:[1,0]
	v_pk_mul_f32 v[30:31], v[30:31], v[234:235] op_sel_hi:[1,0]
	v_mfma_f32_16x16x32_bf16 v[114:117], v[178:181], v[186:189], v[114:117]
	v_pk_mul_f32 v[24:25], v[24:25], v[234:235] op_sel_hi:[1,0]
	v_pk_mul_f32 v[26:27], v[26:27], v[234:235] op_sel_hi:[1,0]
	v_cvt_pk_bf16_f32 v28, v28, v29
	v_cvt_pk_bf16_f32 v29, v30, v31
	v_cvt_pk_bf16_f32 v30, v24, v25
	v_mfma_f32_16x16x32_bf16 v[102:105], v[170:173], v[194:197], v[102:105]
	v_cvt_pk_bf16_f32 v31, v26, v27
	ds_bpermute_b32 v24, v100, v28
	ds_bpermute_b32 v25, v100, v29
	ds_bpermute_b32 v26, v100, v30
	ds_bpermute_b32 v27, v100, v31
	v_mfma_f32_16x16x32_bf16 v[96:99], v[178:181], v[194:197], v[96:99]
	s_waitcnt lgkmcnt(4)
	global_store_dwordx4 v152, v[40:43], s[90:91] nt
	v_add_u32_e32 v152, s0, v152
	v_fmamk_f32 v234, v246, 0x3a800000, v207
	v_rsq_f32_e32 v234, v234
	v_mfma_f32_16x16x32_bf16 v[84:87], v[170:173], v[202:205], v[84:87]
	s_nop 0
	v_mul_f32_e32 v234, s36, v234
	v_pk_mul_f32 v[12:13], v[12:13], v[234:235] op_sel_hi:[1,0]
	v_pk_mul_f32 v[14:15], v[14:15], v[234:235] op_sel_hi:[1,0]
	v_mfma_f32_16x16x32_bf16 v[80:83], v[178:181], v[202:205], v[80:83]
	v_pk_mul_f32 v[8:9], v[8:9], v[234:235] op_sel_hi:[1,0]
	v_pk_mul_f32 v[10:11], v[10:11], v[234:235] op_sel_hi:[1,0]
	v_cvt_pk_bf16_f32 v12, v12, v13
	v_cvt_pk_bf16_f32 v13, v14, v15
	v_cvt_pk_bf16_f32 v14, v8, v9
	v_mfma_f32_16x16x32_bf16 v[68:71], v[170:173], v[226:229], v[68:71]
	v_cvt_pk_bf16_f32 v15, v10, v11
	ds_bpermute_b32 v8, v100, v12
	ds_bpermute_b32 v9, v100, v13
	ds_bpermute_b32 v10, v100, v14
	ds_bpermute_b32 v11, v100, v15
	v_mfma_f32_16x16x32_bf16 v[64:67], v[178:181], v[226:229], v[64:67]
	s_waitcnt lgkmcnt(4)
	global_store_dwordx4 v152, v[24:27], s[90:91] nt
	v_add_u32_e32 v152, s0, v152
	s_waitcnt lgkmcnt(0)
	global_store_dwordx4 v152, v[8:11], s[90:91] nt
	s_setprio 0
	s_barrier
	s_add_i32 s33, s33, s34
	v_lshl_add_u64 v[152:153], s[14:15], 0, v[132:133]
	s_mov_b32 m0, s33
	ds_read_b128 v[182:185], v156 offset:16384
	ds_read_b128 v[186:189], v156 offset:17408
	ds_read_b128 v[190:193], v156 offset:18432
	ds_read_b128 v[194:197], v156 offset:19456
	ds_read_b128 v[198:201], v156 offset:20480
	ds_read_b128 v[202:205], v156 offset:21504
	ds_read_b128 v[208:211], v156 offset:22528
	ds_read_b128 v[226:229], v156 offset:23552
	global_load_lds_dwordx4 v[152:153], off
	s_add_i32 m0, s33, 0x2000
	s_add_u32 s80, s14, 0x40000
	v_lshl_add_u64 v[212:213], s[14:15], 0, v[136:137]
	s_addc_u32 s81, s15, 0
	s_add_i32 s1, s1, s34
	global_load_lds_dwordx4 v[212:213], off
	v_lshl_add_u64 v[230:231], s[80:81], 0, v[132:133]
	s_mov_b32 m0, s1
	v_lshl_add_u64 v[232:233], s[28:29], 0, v[134:135]
	global_load_lds_dwordx4 v[230:231], off
	v_lshl_add_u64 v[230:231], s[80:81], 0, v[136:137]
	s_add_i32 m0, s1, 0x2000
	s_nop 0
	global_load_lds_dwordx4 v[230:231], off
	v_lshl_add_u64 v[230:231], s[28:29], 0, v[130:131]
	s_mov_b32 m0, s41
	s_nop 0
	global_load_lds_dwordx4 v[230:231], off
	s_mov_b32 m0, s60
	s_nop 0
	global_load_lds_dwordx4 v[232:233], off
	v_and_b32_e32 v100, 3, v224
	v_lshlrev_b32_e32 v100, 6, v100
	v_and_or_b32 v100, v224, 60, v100
	v_add_u32_e32 v236, s32, v247
	v_fmamk_f32 v234, v240, 0x3a800000, v207
	v_rsq_f32_e32 v234, v234
	s_nop 0
	v_mul_f32_e32 v234, s36, v234
	v_pk_mul_f32 v[52:53], v[52:53], v[234:235] op_sel_hi:[1,0]
	v_pk_mul_f32 v[54:55], v[54:55], v[234:235] op_sel_hi:[1,0]
	v_pk_mul_f32 v[48:49], v[48:49], v[234:235] op_sel_hi:[1,0]
	v_pk_mul_f32 v[50:51], v[50:51], v[234:235] op_sel_hi:[1,0]
	v_cvt_pk_bf16_f32 v52, v52, v53
	v_cvt_pk_bf16_f32 v53, v54, v55
	v_cvt_pk_bf16_f32 v54, v48, v49
	v_cvt_pk_bf16_f32 v55, v50, v51
	ds_bpermute_b32 v48, v100, v52
	ds_bpermute_b32 v49, v100, v53
	ds_bpermute_b32 v50, v100, v54
	ds_bpermute_b32 v51, v100, v55
	v_fmamk_f32 v234, v244, 0x3a800000, v207
	v_rsq_f32_e32 v234, v234
	s_nop 0
	v_mul_f32_e32 v234, s36, v234
	v_pk_mul_f32 v[36:37], v[36:37], v[234:235] op_sel_hi:[1,0]
	v_pk_mul_f32 v[38:39], v[38:39], v[234:235] op_sel_hi:[1,0]
	v_pk_mul_f32 v[32:33], v[32:33], v[234:235] op_sel_hi:[1,0]
	v_pk_mul_f32 v[34:35], v[34:35], v[234:235] op_sel_hi:[1,0]
	v_cvt_pk_bf16_f32 v36, v36, v37
	v_cvt_pk_bf16_f32 v37, v38, v39
	v_cvt_pk_bf16_f32 v38, v32, v33
	v_cvt_pk_bf16_f32 v39, v34, v35
	ds_bpermute_b32 v32, v100, v36
	ds_bpermute_b32 v33, v100, v37
	ds_bpermute_b32 v34, v100, v38
	ds_bpermute_b32 v35, v100, v39
	s_waitcnt lgkmcnt(4)
	global_store_dwordx4 v236, v[48:51], s[90:91] nt
	v_add_u32_e32 v236, s0, v236
	v_fmamk_f32 v234, v245, 0x3a800000, v207
	v_rsq_f32_e32 v234, v234
	s_nop 0
	v_mul_f32_e32 v234, s36, v234
	v_pk_mul_f32 v[20:21], v[20:21], v[234:235] op_sel_hi:[1,0]
	v_pk_mul_f32 v[22:23], v[22:23], v[234:235] op_sel_hi:[1,0]
	v_pk_mul_f32 v[16:17], v[16:17], v[234:235] op_sel_hi:[1,0]
	v_pk_mul_f32 v[18:19], v[18:19], v[234:235] op_sel_hi:[1,0]
	v_cvt_pk_bf16_f32 v20, v20, v21
	v_cvt_pk_bf16_f32 v21, v22, v23
	v_cvt_pk_bf16_f32 v22, v16, v17
	v_cvt_pk_bf16_f32 v23, v18, v19
	ds_bpermute_b32 v16, v100, v20
	ds_bpermute_b32 v17, v100, v21
	ds_bpermute_b32 v18, v100, v22
	ds_bpermute_b32 v19, v100, v23
	s_waitcnt lgkmcnt(4)
	global_store_dwordx4 v236, v[32:35], s[90:91] nt
	v_add_u32_e32 v236, s0, v236
	v_fmamk_f32 v234, v246, 0x3a800000, v207
	v_rsq_f32_e32 v234, v234
	s_nop 0
	v_mul_f32_e32 v234, s36, v234
	v_pk_mul_f32 v[4:5], v[4:5], v[234:235] op_sel_hi:[1,0]
	v_pk_mul_f32 v[6:7], v[6:7], v[234:235] op_sel_hi:[1,0]
	v_pk_mul_f32 v[0:1], v[0:1], v[234:235] op_sel_hi:[1,0]
	v_pk_mul_f32 v[2:3], v[2:3], v[234:235] op_sel_hi:[1,0]
	v_cvt_pk_bf16_f32 v4, v4, v5
	v_cvt_pk_bf16_f32 v5, v6, v7
	v_cvt_pk_bf16_f32 v6, v0, v1
	v_cvt_pk_bf16_f32 v7, v2, v3
	ds_bpermute_b32 v0, v100, v4
	ds_bpermute_b32 v1, v100, v5
	ds_bpermute_b32 v2, v100, v6
	ds_bpermute_b32 v3, v100, v7
	s_waitcnt lgkmcnt(4)
	global_store_dwordx4 v236, v[16:19], s[90:91] nt
	v_add_u32_e32 v236, s0, v236
	s_waitcnt lgkmcnt(0)
	global_store_dwordx4 v236, v[0:3], s[90:91] nt
	s_lshl_b32 s46, s40, 8
	s_add_i32 s46, s46, s84
	v_or_b32_e32 v100, s46, v139
	v_lshlrev_b32_e32 v100, 2, v100
	global_load_dword v236, v100, s[66:67]
	global_load_dword v237, v100, s[66:67] offset:64
	global_load_dword v238, v100, s[66:67] offset:128
	global_load_dword v239, v100, s[66:67] offset:192
	global_load_dword v240, v100, s[66:67] offset:512
	global_load_dword v244, v100, s[66:67] offset:576
	global_load_dword v245, v100, s[66:67] offset:640
	global_load_dword v246, v100, s[66:67] offset:704
	s_waitcnt vmcnt(32)
	s_waitcnt lgkmcnt(0)
	s_barrier
	s_setprio 1
	s_waitcnt lgkmcnt(0)
	v_mfma_f32_16x16x32_bf16 v[60:63], v[144:147], v[182:185], 0
	v_mfma_f32_16x16x32_bf16 v[56:59], v[158:161], v[182:185], 0
	v_mfma_f32_16x16x32_bf16 v[44:47], v[144:147], v[190:193], 0
	v_mfma_f32_16x16x32_bf16 v[40:43], v[158:161], v[190:193], 0
	v_mfma_f32_16x16x32_bf16 v[28:31], v[144:147], v[198:201], 0
	v_mfma_f32_16x16x32_bf16 v[24:27], v[158:161], v[198:201], 0
	v_mfma_f32_16x16x32_bf16 v[12:15], v[144:147], v[208:211], 0
	v_mfma_f32_16x16x32_bf16 v[8:11], v[158:161], v[208:211], 0
	v_mfma_f32_16x16x32_bf16 v[60:63], v[148:151], v[186:189], v[60:63]
	v_mfma_f32_16x16x32_bf16 v[56:59], v[162:165], v[186:189], v[56:59]
	v_mfma_f32_16x16x32_bf16 v[44:47], v[148:151], v[194:197], v[44:47]
	v_mfma_f32_16x16x32_bf16 v[40:43], v[162:165], v[194:197], v[40:43]
	v_mfma_f32_16x16x32_bf16 v[28:31], v[148:151], v[202:205], v[28:31]
	v_mfma_f32_16x16x32_bf16 v[24:27], v[162:165], v[202:205], v[24:27]
	v_mfma_f32_16x16x32_bf16 v[12:15], v[148:151], v[226:229], v[12:15]
	v_mfma_f32_16x16x32_bf16 v[8:11], v[162:165], v[226:229], v[8:11]
	s_setprio 0
	s_setprio 1
	v_mfma_f32_16x16x32_bf16 v[52:55], v[166:169], v[182:185], 0
	v_mfma_f32_16x16x32_bf16 v[48:51], v[174:177], v[182:185], 0
	v_mfma_f32_16x16x32_bf16 v[36:39], v[166:169], v[190:193], 0
	v_mfma_f32_16x16x32_bf16 v[32:35], v[174:177], v[190:193], 0
	v_mfma_f32_16x16x32_bf16 v[20:23], v[166:169], v[198:201], 0
	v_mfma_f32_16x16x32_bf16 v[16:19], v[174:177], v[198:201], 0
	v_mfma_f32_16x16x32_bf16 v[4:7], v[166:169], v[208:211], 0
	v_mfma_f32_16x16x32_bf16 v[0:3], v[174:177], v[208:211], 0
	v_mfma_f32_16x16x32_bf16 v[52:55], v[170:173], v[186:189], v[52:55]
	v_mfma_f32_16x16x32_bf16 v[48:51], v[178:181], v[186:189], v[48:51]
	v_mfma_f32_16x16x32_bf16 v[36:39], v[170:173], v[194:197], v[36:39]
	v_mfma_f32_16x16x32_bf16 v[32:35], v[178:181], v[194:197], v[32:35]
	v_mfma_f32_16x16x32_bf16 v[20:23], v[170:173], v[202:205], v[20:23]
	v_mfma_f32_16x16x32_bf16 v[16:19], v[178:181], v[202:205], v[16:19]
	v_mfma_f32_16x16x32_bf16 v[4:7], v[170:173], v[226:229], v[4:7]
	v_mfma_f32_16x16x32_bf16 v[0:3], v[178:181], v[226:229], v[0:3]
	s_setprio 0
	s_barrier
	s_add_i32 s1, 0, 0x18000
	v_add_u32_e32 v100, s1, v154
	s_add_i32 s33, 0, 0x1c000
	ds_read_b128 v[144:147], v100
	ds_read_b128 v[148:151], v100 offset:1024
	ds_read_b128 v[158:161], v100 offset:2048
	ds_read_b128 v[162:165], v100 offset:3072
	v_add_u32_e32 v100, s33, v154
	ds_read_b128 v[166:169], v100
	ds_read_b128 v[170:173], v100 offset:1024
	ds_read_b128 v[174:177], v100 offset:2048
	ds_read_b128 v[178:181], v100 offset:3072
	s_add_u32 s28, s28, 0x40000
	s_addc_u32 s29, s29, 0
	s_mov_b32 m0, s61
	v_lshl_add_u64 v[234:235], s[28:29], 0, v[130:131]
	ds_read_b128 v[182:185], v156 offset:32768
	ds_read_b128 v[186:189], v156 offset:33792
	ds_read_b128 v[190:193], v156 offset:34816
	ds_read_b128 v[194:197], v156 offset:35840
	ds_read_b128 v[198:201], v156 offset:36864
	ds_read_b128 v[202:205], v156 offset:37888
	ds_read_b128 v[208:211], v156 offset:38912
	ds_read_b128 v[226:229], v156 offset:39936
	global_load_lds_dwordx4 v[234:235], off
	v_lshl_add_u64 v[234:235], s[28:29], 0, v[134:135]
	s_mov_b32 m0, s69
	s_nop 0
	global_load_lds_dwordx4 v[234:235], off
	s_waitcnt vmcnt(32)
	s_waitcnt lgkmcnt(0)
	s_barrier
	s_setprio 1
	s_waitcnt lgkmcnt(0)
	v_mfma_f32_16x16x32_bf16 v[126:129], v[144:147], v[182:185], v[126:129]
	v_mfma_f32_16x16x32_bf16 v[122:125], v[158:161], v[182:185], v[122:125]
	v_mfma_f32_16x16x32_bf16 v[110:113], v[144:147], v[190:193], v[110:113]
	v_mfma_f32_16x16x32_bf16 v[106:109], v[158:161], v[190:193], v[106:109]
	v_mfma_f32_16x16x32_bf16 v[92:95], v[144:147], v[198:201], v[92:95]
	v_mfma_f32_16x16x32_bf16 v[88:91], v[158:161], v[198:201], v[88:91]
	v_mfma_f32_16x16x32_bf16 v[76:79], v[144:147], v[208:211], v[76:79]
	v_mfma_f32_16x16x32_bf16 v[72:75], v[158:161], v[208:211], v[72:75]
	v_mfma_f32_16x16x32_bf16 v[126:129], v[148:151], v[186:189], v[126:129]
	v_mfma_f32_16x16x32_bf16 v[122:125], v[162:165], v[186:189], v[122:125]
	v_mfma_f32_16x16x32_bf16 v[110:113], v[148:151], v[194:197], v[110:113]
	v_mfma_f32_16x16x32_bf16 v[106:109], v[162:165], v[194:197], v[106:109]
	v_mfma_f32_16x16x32_bf16 v[92:95], v[148:151], v[202:205], v[92:95]
	v_mfma_f32_16x16x32_bf16 v[88:91], v[162:165], v[202:205], v[88:91]
	v_mfma_f32_16x16x32_bf16 v[76:79], v[148:151], v[226:229], v[76:79]
	v_mfma_f32_16x16x32_bf16 v[72:75], v[162:165], v[226:229], v[72:75]
	s_setprio 0
	s_setprio 1
	v_mfma_f32_16x16x32_bf16 v[118:121], v[166:169], v[182:185], v[118:121]
	v_mfma_f32_16x16x32_bf16 v[114:117], v[174:177], v[182:185], v[114:117]
	v_mfma_f32_16x16x32_bf16 v[102:105], v[166:169], v[190:193], v[102:105]
	v_mfma_f32_16x16x32_bf16 v[96:99], v[174:177], v[190:193], v[96:99]
	v_mfma_f32_16x16x32_bf16 v[84:87], v[166:169], v[198:201], v[84:87]
	v_mfma_f32_16x16x32_bf16 v[80:83], v[174:177], v[198:201], v[80:83]
	v_mfma_f32_16x16x32_bf16 v[68:71], v[166:169], v[208:211], v[68:71]
	v_mfma_f32_16x16x32_bf16 v[64:67], v[174:177], v[208:211], v[64:67]
	v_mfma_f32_16x16x32_bf16 v[118:121], v[170:173], v[186:189], v[118:121]
	v_mfma_f32_16x16x32_bf16 v[114:117], v[178:181], v[186:189], v[114:117]
	v_mfma_f32_16x16x32_bf16 v[102:105], v[170:173], v[194:197], v[102:105]
	v_mfma_f32_16x16x32_bf16 v[96:99], v[178:181], v[194:197], v[96:99]
	v_mfma_f32_16x16x32_bf16 v[84:87], v[170:173], v[202:205], v[84:87]
	v_mfma_f32_16x16x32_bf16 v[80:83], v[178:181], v[202:205], v[80:83]
	v_mfma_f32_16x16x32_bf16 v[68:71], v[170:173], v[226:229], v[68:71]
	v_mfma_f32_16x16x32_bf16 v[64:67], v[178:181], v[226:229], v[64:67]
	s_setprio 0
	s_barrier
	s_add_i32 s1, s1, s34
	v_lshl_add_u64 v[152:153], v[152:153], 0, s[86:87]
	s_mov_b32 m0, s1
	ds_read_b128 v[182:185], v156 offset:49152
	ds_read_b128 v[186:189], v156 offset:50176
	ds_read_b128 v[190:193], v156 offset:51200
	ds_read_b128 v[194:197], v156 offset:52224
	ds_read_b128 v[198:201], v156 offset:53248
	ds_read_b128 v[202:205], v156 offset:54272
	ds_read_b128 v[208:211], v156 offset:55296
	ds_read_b128 v[226:229], v156 offset:56320
	global_load_lds_dwordx4 v[152:153], off
	s_add_i32 m0, s1, 0x2000
	s_add_u32 s14, s14, 0x40080
	v_lshl_add_u64 v[152:153], v[212:213], 0, s[86:87]
	s_addc_u32 s15, s15, 0
	s_add_i32 s1, s33, s34
	global_load_lds_dwordx4 v[152:153], off
	v_lshl_add_u64 v[152:153], s[14:15], 0, v[132:133]
	s_mov_b32 m0, s1
	s_nop 0
	global_load_lds_dwordx4 v[152:153], off
	v_lshl_add_u64 v[152:153], s[14:15], 0, v[136:137]
	s_add_i32 m0, s1, 0x2000
	s_nop 0
	global_load_lds_dwordx4 v[152:153], off
	v_lshl_add_u64 v[152:153], v[230:231], 0, s[86:87]
	s_mov_b32 m0, s89
	s_nop 0
	global_load_lds_dwordx4 v[152:153], off
	v_lshl_add_u64 v[152:153], v[232:233], 0, s[86:87]
	s_mov_b32 m0, s92
	s_nop 0
	global_load_lds_dwordx4 v[152:153], off
	s_waitcnt vmcnt(20)
	s_waitcnt lgkmcnt(0)
	s_barrier
	s_setprio 1
	s_waitcnt lgkmcnt(0)
	v_mfma_f32_16x16x32_bf16 v[60:63], v[144:147], v[182:185], v[60:63]
	v_mfma_f32_16x16x32_bf16 v[56:59], v[158:161], v[182:185], v[56:59]
	v_mfma_f32_16x16x32_bf16 v[44:47], v[144:147], v[190:193], v[44:47]
	v_mfma_f32_16x16x32_bf16 v[40:43], v[158:161], v[190:193], v[40:43]
	v_mfma_f32_16x16x32_bf16 v[28:31], v[144:147], v[198:201], v[28:31]
	v_mfma_f32_16x16x32_bf16 v[24:27], v[158:161], v[198:201], v[24:27]
	v_mfma_f32_16x16x32_bf16 v[12:15], v[144:147], v[208:211], v[12:15]
	v_mfma_f32_16x16x32_bf16 v[8:11], v[158:161], v[208:211], v[8:11]
	v_mfma_f32_16x16x32_bf16 v[60:63], v[148:151], v[186:189], v[60:63]
	v_mfma_f32_16x16x32_bf16 v[56:59], v[162:165], v[186:189], v[56:59]
	v_mfma_f32_16x16x32_bf16 v[44:47], v[148:151], v[194:197], v[44:47]
	v_mfma_f32_16x16x32_bf16 v[40:43], v[162:165], v[194:197], v[40:43]
	v_mfma_f32_16x16x32_bf16 v[28:31], v[148:151], v[202:205], v[28:31]
	v_mfma_f32_16x16x32_bf16 v[24:27], v[162:165], v[202:205], v[24:27]
	v_mfma_f32_16x16x32_bf16 v[12:15], v[148:151], v[226:229], v[12:15]
	v_mfma_f32_16x16x32_bf16 v[8:11], v[162:165], v[226:229], v[8:11]
	s_setprio 0
	s_setprio 1
	v_mfma_f32_16x16x32_bf16 v[52:55], v[166:169], v[182:185], v[52:55]
	v_mfma_f32_16x16x32_bf16 v[48:51], v[174:177], v[182:185], v[48:51]
	v_mfma_f32_16x16x32_bf16 v[36:39], v[166:169], v[190:193], v[36:39]
	v_mfma_f32_16x16x32_bf16 v[32:35], v[174:177], v[190:193], v[32:35]
	v_mfma_f32_16x16x32_bf16 v[20:23], v[166:169], v[198:201], v[20:23]
	v_mfma_f32_16x16x32_bf16 v[16:19], v[174:177], v[198:201], v[16:19]
	v_mfma_f32_16x16x32_bf16 v[4:7], v[166:169], v[208:211], v[4:7]
	v_mfma_f32_16x16x32_bf16 v[0:3], v[174:177], v[208:211], v[0:3]
	v_mfma_f32_16x16x32_bf16 v[52:55], v[170:173], v[186:189], v[52:55]
	v_mfma_f32_16x16x32_bf16 v[48:51], v[178:181], v[186:189], v[48:51]
	v_mfma_f32_16x16x32_bf16 v[36:39], v[170:173], v[194:197], v[36:39]
	v_mfma_f32_16x16x32_bf16 v[32:35], v[178:181], v[194:197], v[32:35]
	v_mfma_f32_16x16x32_bf16 v[20:23], v[170:173], v[202:205], v[20:23]
	v_mfma_f32_16x16x32_bf16 v[16:19], v[178:181], v[202:205], v[16:19]
	v_mfma_f32_16x16x32_bf16 v[4:7], v[170:173], v[226:229], v[4:7]
	v_mfma_f32_16x16x32_bf16 v[0:3], v[178:181], v[226:229], v[0:3]
	s_setprio 0
	s_barrier
	s_add_i32 s73, s73, 2
	s_add_u32 s12, s12, 0x100
	s_addc_u32 s13, s13, 0
	s_add_u32 s54, s54, 0x100
	s_addc_u32 s55, s55, 0
